# combination: INPROJ blocked raster + ATTN P.V on f32 matrix cores + ATTN item-top waits relaxed to vmcnt(4) + SSMB C-projection with hoisted LDS reads and two MFMA chains
# speedup vs baseline: 1.0070x; 1.0038x over previous
; template <bool FULL>
; DI void ssm_item(const P& p, int l, int item, char* smem) {
;     ...
;     for (int t = 0; t < 16; ++t) {
;       const float4* up = (const float4*)(us + t * 16);
;       const float4 u0 = up[0], u1 = up[1], u2 = up[2], u3 = up[3];
;       const float uu[16] = {u0.x, u0.y, u0.z, u0.w, u1.x, u1.y, u1.z, u1.w, u2.x, u2.y, u2.z, u2.w, u3.x, u3.y, u3.z, u3.w};
;       float br = 0.f, bi = 0.f;
; #pragma unroll
;       for (int i = 0; i < 16; ++i) { br = fmaf(bbr[i], uu[i], br); bi = fmaf(bbi[i], uu[i], bi); }
;       const float nhr = ar * hr - ai * hi + br, nhi = ar * hi + ai * hr + bi;
;       hr = nhr; hi = nhi;
;       if (FULL) { H[t * 132 + lane] = hr; H[t * 132 + 64 + lane] = hi; }
;     }
.LBB0_173:
	v_add_u32_e32 v154, v86, v46
	ds_read_b128 v[112:115], v46 offset:8448
	ds_read_b128 v[116:119], v46 offset:8464
	ds_read_b128 v[120:123], v46 offset:8480
	ds_read_b128 v[124:127], v46 offset:8496
	ds_read_b128 v[128:131], v46 offset:8512
	ds_read_b128 v[132:135], v46 offset:8528
	ds_read_b128 v[136:139], v46 offset:8544
	ds_read_b128 v[140:143], v46 offset:8560
	s_waitcnt lgkmcnt(4)
	v_mul_f32_e32 v144, v12, v112
	v_mul_f32_e32 v145, v13, v112
	v_mul_f32_e32 v146, v4, v116
	v_mul_f32_e32 v147, v5, v116
	v_mul_f32_e32 v148, v32, v120
	v_mul_f32_e32 v149, v33, v120
	v_mul_f32_e32 v150, v24, v124
	v_mul_f32_e32 v151, v25, v124
	v_fmac_f32_e32 v144, v14, v113
	v_fmac_f32_e32 v145, v15, v113
	v_fmac_f32_e32 v146, v6, v117
	v_fmac_f32_e32 v147, v7, v117
	v_fmac_f32_e32 v148, v34, v121
	v_fmac_f32_e32 v149, v35, v121
	v_fmac_f32_e32 v150, v26, v125
	v_fmac_f32_e32 v151, v27, v125
	v_fmac_f32_e32 v144, v8, v114
	v_fmac_f32_e32 v145, v9, v114
	v_fmac_f32_e32 v146, v0, v118
	v_fmac_f32_e32 v147, v1, v118
	v_fmac_f32_e32 v148, v28, v122
	v_fmac_f32_e32 v149, v29, v122
	v_fmac_f32_e32 v150, v20, v126
	v_fmac_f32_e32 v151, v21, v126
	v_fmac_f32_e32 v144, v10, v115
	v_fmac_f32_e32 v145, v11, v115
	v_fmac_f32_e32 v146, v2, v119
	v_fmac_f32_e32 v147, v3, v119
	v_fmac_f32_e32 v148, v30, v123
	v_fmac_f32_e32 v149, v31, v123
	v_fmac_f32_e32 v150, v22, v127
	v_fmac_f32_e32 v151, v23, v127
	v_add_f32_e32 v144, v144, v146
	v_add_f32_e32 v145, v145, v147
	v_add_f32_e32 v148, v148, v150
	v_add_f32_e32 v149, v149, v151
	v_add_f32_e32 v144, v144, v148
	v_add_f32_e32 v145, v145, v149
	v_fma_f32 v152, -v17, v37, v144
	v_fma_f32 v153, v17, v36, v145
	v_fma_f32 v36, v16, v36, v152
	v_fma_f32 v37, v16, v37, v153
	ds_write_b32 v154, v36 offset:0
	ds_write_b32 v154, v37 offset:256
	ds_read_b128 v[112:115], v46 offset:8576
	ds_read_b128 v[116:119], v46 offset:8592
	ds_read_b128 v[120:123], v46 offset:8608
	ds_read_b128 v[124:127], v46 offset:8624
	s_waitcnt lgkmcnt(6)
	v_mul_f32_e32 v144, v12, v128
	v_mul_f32_e32 v145, v13, v128
	v_mul_f32_e32 v146, v4, v132
	v_mul_f32_e32 v147, v5, v132
	v_mul_f32_e32 v148, v32, v136
	v_mul_f32_e32 v149, v33, v136
	v_mul_f32_e32 v150, v24, v140
	v_mul_f32_e32 v151, v25, v140
	v_fmac_f32_e32 v144, v14, v129
	v_fmac_f32_e32 v145, v15, v129
	v_fmac_f32_e32 v146, v6, v133
	v_fmac_f32_e32 v147, v7, v133
	v_fmac_f32_e32 v148, v34, v137
	v_fmac_f32_e32 v149, v35, v137
	v_fmac_f32_e32 v150, v26, v141
	v_fmac_f32_e32 v151, v27, v141
	v_fmac_f32_e32 v144, v8, v130
	v_fmac_f32_e32 v145, v9, v130
	v_fmac_f32_e32 v146, v0, v134
	v_fmac_f32_e32 v147, v1, v134
	v_fmac_f32_e32 v148, v28, v138
	v_fmac_f32_e32 v149, v29, v138
	v_fmac_f32_e32 v150, v20, v142
	v_fmac_f32_e32 v151, v21, v142
	v_fmac_f32_e32 v144, v10, v131
	v_fmac_f32_e32 v145, v11, v131
	v_fmac_f32_e32 v146, v2, v135
	v_fmac_f32_e32 v147, v3, v135
	v_fmac_f32_e32 v148, v30, v139
	v_fmac_f32_e32 v149, v31, v139
	v_fmac_f32_e32 v150, v22, v143
	v_fmac_f32_e32 v151, v23, v143
	v_add_f32_e32 v144, v144, v146
	v_add_f32_e32 v145, v145, v147
	v_add_f32_e32 v148, v148, v150
	v_add_f32_e32 v149, v149, v151
	v_add_f32_e32 v144, v144, v148
	v_add_f32_e32 v145, v145, v149
	v_fma_f32 v152, -v17, v37, v144
	v_fma_f32 v153, v17, v36, v145
	v_fma_f32 v36, v16, v36, v152
	v_fma_f32 v37, v16, v37, v153
	ds_write_b32 v154, v36 offset:528
	ds_write_b32 v154, v37 offset:784
	ds_read_b128 v[128:131], v46 offset:8640
	ds_read_b128 v[132:135], v46 offset:8656
	ds_read_b128 v[136:139], v46 offset:8672
	ds_read_b128 v[140:143], v46 offset:8688
	s_waitcnt lgkmcnt(6)
	v_mul_f32_e32 v144, v12, v112
	v_mul_f32_e32 v145, v13, v112
	v_mul_f32_e32 v146, v4, v116
	v_mul_f32_e32 v147, v5, v116
	v_mul_f32_e32 v148, v32, v120
	v_mul_f32_e32 v149, v33, v120
	v_mul_f32_e32 v150, v24, v124
	v_mul_f32_e32 v151, v25, v124
	v_fmac_f32_e32 v144, v14, v113
	v_fmac_f32_e32 v145, v15, v113
	v_fmac_f32_e32 v146, v6, v117
	v_fmac_f32_e32 v147, v7, v117
	v_fmac_f32_e32 v148, v34, v121
	v_fmac_f32_e32 v149, v35, v121
	v_fmac_f32_e32 v150, v26, v125
	v_fmac_f32_e32 v151, v27, v125
	v_fmac_f32_e32 v144, v8, v114
	v_fmac_f32_e32 v145, v9, v114
	v_fmac_f32_e32 v146, v0, v118
	v_fmac_f32_e32 v147, v1, v118
	v_fmac_f32_e32 v148, v28, v122
	v_fmac_f32_e32 v149, v29, v122
	v_fmac_f32_e32 v150, v20, v126
	v_fmac_f32_e32 v151, v21, v126
	v_fmac_f32_e32 v144, v10, v115
	v_fmac_f32_e32 v145, v11, v115
	v_fmac_f32_e32 v146, v2, v119
	v_fmac_f32_e32 v147, v3, v119
	v_fmac_f32_e32 v148, v30, v123
	v_fmac_f32_e32 v149, v31, v123
	v_fmac_f32_e32 v150, v22, v127
	v_fmac_f32_e32 v151, v23, v127
	v_add_f32_e32 v144, v144, v146
	v_add_f32_e32 v145, v145, v147
	v_add_f32_e32 v148, v148, v150
	v_add_f32_e32 v149, v149, v151
	v_add_f32_e32 v144, v144, v148
	v_add_f32_e32 v145, v145, v149
	v_fma_f32 v152, -v17, v37, v144
	v_fma_f32 v153, v17, v36, v145
	v_fma_f32 v36, v16, v36, v152
	v_fma_f32 v37, v16, v37, v153
	ds_write_b32 v154, v36 offset:1056
	ds_write_b32 v154, v37 offset:1312
	ds_read_b128 v[112:115], v46 offset:8704
	ds_read_b128 v[116:119], v46 offset:8720
	ds_read_b128 v[120:123], v46 offset:8736
	ds_read_b128 v[124:127], v46 offset:8752
	s_waitcnt lgkmcnt(6)
; template <bool FULL>
; DI void ssm_item(const P& p, int l, int item, char* smem) {
;     ...
;     for (int t = 0; t < 16; ++t) {
;       const float4* up = (const float4*)(us + t * 16);
;       const float4 u0 = up[0], u1 = up[1], u2 = up[2], u3 = up[3];
;       const float uu[16] = {u0.x, u0.y, u0.z, u0.w, u1.x, u1.y, u1.z, u1.w, u2.x, u2.y, u2.z, u2.w, u3.x, u3.y, u3.z, u3.w};
;       float br = 0.f, bi = 0.f;
; #pragma unroll
;       for (int i = 0; i < 16; ++i) { br = fmaf(bbr[i], uu[i], br); bi = fmaf(bbi[i], uu[i], bi); }
;       const float nhr = ar * hr - ai * hi + br, nhi = ar * hi + ai * hr + bi;
;       hr = nhr; hi = nhi;
;       if (FULL) { H[t * 132 + lane] = hr; H[t * 132 + 64 + lane] = hi; }
;     }
	v_mul_f32_e32 v144, v12, v128
	v_mul_f32_e32 v145, v13, v128
	v_mul_f32_e32 v146, v4, v132
	v_mul_f32_e32 v147, v5, v132
	v_mul_f32_e32 v148, v32, v136
	v_mul_f32_e32 v149, v33, v136
	v_mul_f32_e32 v150, v24, v140
	v_mul_f32_e32 v151, v25, v140
	v_fmac_f32_e32 v144, v14, v129
	v_fmac_f32_e32 v145, v15, v129
	v_fmac_f32_e32 v146, v6, v133
	v_fmac_f32_e32 v147, v7, v133
	v_fmac_f32_e32 v148, v34, v137
	v_fmac_f32_e32 v149, v35, v137
	v_fmac_f32_e32 v150, v26, v141
	v_fmac_f32_e32 v151, v27, v141
	v_fmac_f32_e32 v144, v8, v130
	v_fmac_f32_e32 v145, v9, v130
	v_fmac_f32_e32 v146, v0, v134
	v_fmac_f32_e32 v147, v1, v134
	v_fmac_f32_e32 v148, v28, v138
	v_fmac_f32_e32 v149, v29, v138
	v_fmac_f32_e32 v150, v20, v142
	v_fmac_f32_e32 v151, v21, v142
	v_fmac_f32_e32 v144, v10, v131
	v_fmac_f32_e32 v145, v11, v131
	v_fmac_f32_e32 v146, v2, v135
	v_fmac_f32_e32 v147, v3, v135
	v_fmac_f32_e32 v148, v30, v139
	v_fmac_f32_e32 v149, v31, v139
	v_fmac_f32_e32 v150, v22, v143
	v_fmac_f32_e32 v151, v23, v143
	v_add_f32_e32 v144, v144, v146
	v_add_f32_e32 v145, v145, v147
	v_add_f32_e32 v148, v148, v150
	v_add_f32_e32 v149, v149, v151
	v_add_f32_e32 v144, v144, v148
	v_add_f32_e32 v145, v145, v149
	v_fma_f32 v152, -v17, v37, v144
	v_fma_f32 v153, v17, v36, v145
	v_fma_f32 v36, v16, v36, v152
	v_fma_f32 v37, v16, v37, v153
	ds_write_b32 v154, v36 offset:1584
	ds_write_b32 v154, v37 offset:1840
	ds_read_b128 v[128:131], v46 offset:8768
	ds_read_b128 v[132:135], v46 offset:8784
	ds_read_b128 v[136:139], v46 offset:8800
	ds_read_b128 v[140:143], v46 offset:8816
	s_waitcnt lgkmcnt(6)
	v_mul_f32_e32 v144, v12, v112
	v_mul_f32_e32 v145, v13, v112
	v_mul_f32_e32 v146, v4, v116
	v_mul_f32_e32 v147, v5, v116
	v_mul_f32_e32 v148, v32, v120
	v_mul_f32_e32 v149, v33, v120
	v_mul_f32_e32 v150, v24, v124
	v_mul_f32_e32 v151, v25, v124
	v_fmac_f32_e32 v144, v14, v113
	v_fmac_f32_e32 v145, v15, v113
	v_fmac_f32_e32 v146, v6, v117
	v_fmac_f32_e32 v147, v7, v117
	v_fmac_f32_e32 v148, v34, v121
	v_fmac_f32_e32 v149, v35, v121
	v_fmac_f32_e32 v150, v26, v125
	v_fmac_f32_e32 v151, v27, v125
	v_fmac_f32_e32 v144, v8, v114
	v_fmac_f32_e32 v145, v9, v114
	v_fmac_f32_e32 v146, v0, v118
	v_fmac_f32_e32 v147, v1, v118
	v_fmac_f32_e32 v148, v28, v122
	v_fmac_f32_e32 v149, v29, v122
	v_fmac_f32_e32 v150, v20, v126
	v_fmac_f32_e32 v151, v21, v126
	v_fmac_f32_e32 v144, v10, v115
	v_fmac_f32_e32 v145, v11, v115
	v_fmac_f32_e32 v146, v2, v119
	v_fmac_f32_e32 v147, v3, v119
	v_fmac_f32_e32 v148, v30, v123
	v_fmac_f32_e32 v149, v31, v123
	v_fmac_f32_e32 v150, v22, v127
	v_fmac_f32_e32 v151, v23, v127
	v_add_f32_e32 v144, v144, v146
	v_add_f32_e32 v145, v145, v147
	v_add_f32_e32 v148, v148, v150
	v_add_f32_e32 v149, v149, v151
	v_add_f32_e32 v144, v144, v148
	v_add_f32_e32 v145, v145, v149
	v_fma_f32 v152, -v17, v37, v144
	v_fma_f32 v153, v17, v36, v145
	v_fma_f32 v36, v16, v36, v152
	v_fma_f32 v37, v16, v37, v153
	ds_write_b32 v154, v36 offset:2112
	ds_write_b32 v154, v37 offset:2368
	ds_read_b128 v[112:115], v46 offset:8832
	ds_read_b128 v[116:119], v46 offset:8848
	ds_read_b128 v[120:123], v46 offset:8864
	ds_read_b128 v[124:127], v46 offset:8880
	s_waitcnt lgkmcnt(6)
	v_mul_f32_e32 v144, v12, v128
	v_mul_f32_e32 v145, v13, v128
	v_mul_f32_e32 v146, v4, v132
	v_mul_f32_e32 v147, v5, v132
	v_mul_f32_e32 v148, v32, v136
	v_mul_f32_e32 v149, v33, v136
	v_mul_f32_e32 v150, v24, v140
	v_mul_f32_e32 v151, v25, v140
	v_fmac_f32_e32 v144, v14, v129
	v_fmac_f32_e32 v145, v15, v129
	v_fmac_f32_e32 v146, v6, v133
	v_fmac_f32_e32 v147, v7, v133
	v_fmac_f32_e32 v148, v34, v137
	v_fmac_f32_e32 v149, v35, v137
	v_fmac_f32_e32 v150, v26, v141
	v_fmac_f32_e32 v151, v27, v141
	v_fmac_f32_e32 v144, v8, v130
	v_fmac_f32_e32 v145, v9, v130
	v_fmac_f32_e32 v146, v0, v134
	v_fmac_f32_e32 v147, v1, v134
	v_fmac_f32_e32 v148, v28, v138
	v_fmac_f32_e32 v149, v29, v138
	v_fmac_f32_e32 v150, v20, v142
	v_fmac_f32_e32 v151, v21, v142
	v_fmac_f32_e32 v144, v10, v131
	v_fmac_f32_e32 v145, v11, v131
	v_fmac_f32_e32 v146, v2, v135
	v_fmac_f32_e32 v147, v3, v135
	v_fmac_f32_e32 v148, v30, v139
	v_fmac_f32_e32 v149, v31, v139
	v_fmac_f32_e32 v150, v22, v143
	v_fmac_f32_e32 v151, v23, v143
	v_add_f32_e32 v144, v144, v146
	v_add_f32_e32 v145, v145, v147
	v_add_f32_e32 v148, v148, v150
	v_add_f32_e32 v149, v149, v151
	v_add_f32_e32 v144, v144, v148
	v_add_f32_e32 v145, v145, v149
	v_fma_f32 v152, -v17, v37, v144
	v_fma_f32 v153, v17, v36, v145
	v_fma_f32 v36, v16, v36, v152
	v_fma_f32 v37, v16, v37, v153
	ds_write_b32 v154, v36 offset:2640
	ds_write_b32 v154, v37 offset:2896
	ds_read_b128 v[128:131], v46 offset:8896
	ds_read_b128 v[132:135], v46 offset:8912
	ds_read_b128 v[136:139], v46 offset:8928
	ds_read_b128 v[140:143], v46 offset:8944
	s_waitcnt lgkmcnt(6)
	v_mul_f32_e32 v144, v12, v112
	v_mul_f32_e32 v145, v13, v112
	v_mul_f32_e32 v146, v4, v116
	v_mul_f32_e32 v147, v5, v116
	v_mul_f32_e32 v148, v32, v120
	v_mul_f32_e32 v149, v33, v120
	v_mul_f32_e32 v150, v24, v124
	v_mul_f32_e32 v151, v25, v124
	v_fmac_f32_e32 v144, v14, v113
	v_fmac_f32_e32 v145, v15, v113
	v_fmac_f32_e32 v146, v6, v117
	v_fmac_f32_e32 v147, v7, v117
	v_fmac_f32_e32 v148, v34, v121
	v_fmac_f32_e32 v149, v35, v121
	v_fmac_f32_e32 v150, v26, v125
	v_fmac_f32_e32 v151, v27, v125
	v_fmac_f32_e32 v144, v8, v114
	v_fmac_f32_e32 v145, v9, v114
	v_fmac_f32_e32 v146, v0, v118
	v_fmac_f32_e32 v147, v1, v118
	v_fmac_f32_e32 v148, v28, v122
	v_fmac_f32_e32 v149, v29, v122
	v_fmac_f32_e32 v150, v20, v126
	v_fmac_f32_e32 v151, v21, v126
	v_fmac_f32_e32 v144, v10, v115
	v_fmac_f32_e32 v145, v11, v115
	v_fmac_f32_e32 v146, v2, v119
	v_fmac_f32_e32 v147, v3, v119
	v_fmac_f32_e32 v148, v30, v123
	v_fmac_f32_e32 v149, v31, v123
	v_fmac_f32_e32 v150, v22, v127
	v_fmac_f32_e32 v151, v23, v127
	v_add_f32_e32 v144, v144, v146
	v_add_f32_e32 v145, v145, v147
	v_add_f32_e32 v148, v148, v150
	v_add_f32_e32 v149, v149, v151
	v_add_f32_e32 v144, v144, v148
	v_add_f32_e32 v145, v145, v149
	v_fma_f32 v152, -v17, v37, v144
	v_fma_f32 v153, v17, v36, v145
	v_fma_f32 v36, v16, v36, v152
	v_fma_f32 v37, v16, v37, v153
	ds_write_b32 v154, v36 offset:3168
	ds_write_b32 v154, v37 offset:3424
	ds_read_b128 v[112:115], v46 offset:8960
	ds_read_b128 v[116:119], v46 offset:8976
	ds_read_b128 v[120:123], v46 offset:8992
	ds_read_b128 v[124:127], v46 offset:9008
	s_waitcnt lgkmcnt(6)
; template <bool FULL>
; DI void ssm_item(const P& p, int l, int item, char* smem) {
;     ...
;     for (int t = 0; t < 16; ++t) {
;       const float4* up = (const float4*)(us + t * 16);
;       const float4 u0 = up[0], u1 = up[1], u2 = up[2], u3 = up[3];
;       const float uu[16] = {u0.x, u0.y, u0.z, u0.w, u1.x, u1.y, u1.z, u1.w, u2.x, u2.y, u2.z, u2.w, u3.x, u3.y, u3.z, u3.w};
;       float br = 0.f, bi = 0.f;
; #pragma unroll
;       for (int i = 0; i < 16; ++i) { br = fmaf(bbr[i], uu[i], br); bi = fmaf(bbi[i], uu[i], bi); }
;       const float nhr = ar * hr - ai * hi + br, nhi = ar * hi + ai * hr + bi;
;       hr = nhr; hi = nhi;
;       if (FULL) { H[t * 132 + lane] = hr; H[t * 132 + 64 + lane] = hi; }
;     }
	v_mul_f32_e32 v144, v12, v128
	v_mul_f32_e32 v145, v13, v128
	v_mul_f32_e32 v146, v4, v132
	v_mul_f32_e32 v147, v5, v132
	v_mul_f32_e32 v148, v32, v136
	v_mul_f32_e32 v149, v33, v136
	v_mul_f32_e32 v150, v24, v140
	v_mul_f32_e32 v151, v25, v140
	v_fmac_f32_e32 v144, v14, v129
	v_fmac_f32_e32 v145, v15, v129
	v_fmac_f32_e32 v146, v6, v133
	v_fmac_f32_e32 v147, v7, v133
	v_fmac_f32_e32 v148, v34, v137
	v_fmac_f32_e32 v149, v35, v137
	v_fmac_f32_e32 v150, v26, v141
	v_fmac_f32_e32 v151, v27, v141
	v_fmac_f32_e32 v144, v8, v130
	v_fmac_f32_e32 v145, v9, v130
	v_fmac_f32_e32 v146, v0, v134
	v_fmac_f32_e32 v147, v1, v134
	v_fmac_f32_e32 v148, v28, v138
	v_fmac_f32_e32 v149, v29, v138
	v_fmac_f32_e32 v150, v20, v142
	v_fmac_f32_e32 v151, v21, v142
	v_fmac_f32_e32 v144, v10, v131
	v_fmac_f32_e32 v145, v11, v131
	v_fmac_f32_e32 v146, v2, v135
	v_fmac_f32_e32 v147, v3, v135
	v_fmac_f32_e32 v148, v30, v139
	v_fmac_f32_e32 v149, v31, v139
	v_fmac_f32_e32 v150, v22, v143
	v_fmac_f32_e32 v151, v23, v143
	v_add_f32_e32 v144, v144, v146
	v_add_f32_e32 v145, v145, v147
	v_add_f32_e32 v148, v148, v150
	v_add_f32_e32 v149, v149, v151
	v_add_f32_e32 v144, v144, v148
	v_add_f32_e32 v145, v145, v149
	v_fma_f32 v152, -v17, v37, v144
	v_fma_f32 v153, v17, v36, v145
	v_fma_f32 v36, v16, v36, v152
	v_fma_f32 v37, v16, v37, v153
	ds_write_b32 v154, v36 offset:3696
	ds_write_b32 v154, v37 offset:3952
	ds_read_b128 v[128:131], v46 offset:9024
	ds_read_b128 v[132:135], v46 offset:9040
	ds_read_b128 v[136:139], v46 offset:9056
	ds_read_b128 v[140:143], v46 offset:9072
	s_waitcnt lgkmcnt(6)
	v_mul_f32_e32 v144, v12, v112
	v_mul_f32_e32 v145, v13, v112
	v_mul_f32_e32 v146, v4, v116
	v_mul_f32_e32 v147, v5, v116
	v_mul_f32_e32 v148, v32, v120
	v_mul_f32_e32 v149, v33, v120
	v_mul_f32_e32 v150, v24, v124
	v_mul_f32_e32 v151, v25, v124
	v_fmac_f32_e32 v144, v14, v113
	v_fmac_f32_e32 v145, v15, v113
	v_fmac_f32_e32 v146, v6, v117
	v_fmac_f32_e32 v147, v7, v117
	v_fmac_f32_e32 v148, v34, v121
	v_fmac_f32_e32 v149, v35, v121
	v_fmac_f32_e32 v150, v26, v125
	v_fmac_f32_e32 v151, v27, v125
	v_fmac_f32_e32 v144, v8, v114
	v_fmac_f32_e32 v145, v9, v114
	v_fmac_f32_e32 v146, v0, v118
	v_fmac_f32_e32 v147, v1, v118
	v_fmac_f32_e32 v148, v28, v122
	v_fmac_f32_e32 v149, v29, v122
	v_fmac_f32_e32 v150, v20, v126
	v_fmac_f32_e32 v151, v21, v126
	v_fmac_f32_e32 v144, v10, v115
	v_fmac_f32_e32 v145, v11, v115
	v_fmac_f32_e32 v146, v2, v119
	v_fmac_f32_e32 v147, v3, v119
	v_fmac_f32_e32 v148, v30, v123
	v_fmac_f32_e32 v149, v31, v123
	v_fmac_f32_e32 v150, v22, v127
	v_fmac_f32_e32 v151, v23, v127
	v_add_f32_e32 v144, v144, v146
	v_add_f32_e32 v145, v145, v147
	v_add_f32_e32 v148, v148, v150
	v_add_f32_e32 v149, v149, v151
	v_add_f32_e32 v144, v144, v148
	v_add_f32_e32 v145, v145, v149
	v_fma_f32 v152, -v17, v37, v144
	v_fma_f32 v153, v17, v36, v145
	v_fma_f32 v36, v16, v36, v152
	v_fma_f32 v37, v16, v37, v153
	ds_write_b32 v154, v36 offset:4224
	ds_write_b32 v154, v37 offset:4480
	ds_read_b128 v[112:115], v46 offset:9088
	ds_read_b128 v[116:119], v46 offset:9104
	ds_read_b128 v[120:123], v46 offset:9120
	ds_read_b128 v[124:127], v46 offset:9136
	s_waitcnt lgkmcnt(6)
	v_mul_f32_e32 v144, v12, v128
	v_mul_f32_e32 v145, v13, v128
	v_mul_f32_e32 v146, v4, v132
	v_mul_f32_e32 v147, v5, v132
	v_mul_f32_e32 v148, v32, v136
	v_mul_f32_e32 v149, v33, v136
	v_mul_f32_e32 v150, v24, v140
	v_mul_f32_e32 v151, v25, v140
	v_fmac_f32_e32 v144, v14, v129
	v_fmac_f32_e32 v145, v15, v129
	v_fmac_f32_e32 v146, v6, v133
	v_fmac_f32_e32 v147, v7, v133
	v_fmac_f32_e32 v148, v34, v137
	v_fmac_f32_e32 v149, v35, v137
	v_fmac_f32_e32 v150, v26, v141
	v_fmac_f32_e32 v151, v27, v141
	v_fmac_f32_e32 v144, v8, v130
	v_fmac_f32_e32 v145, v9, v130
	v_fmac_f32_e32 v146, v0, v134
	v_fmac_f32_e32 v147, v1, v134
	v_fmac_f32_e32 v148, v28, v138
	v_fmac_f32_e32 v149, v29, v138
	v_fmac_f32_e32 v150, v20, v142
	v_fmac_f32_e32 v151, v21, v142
	v_fmac_f32_e32 v144, v10, v131
	v_fmac_f32_e32 v145, v11, v131
	v_fmac_f32_e32 v146, v2, v135
	v_fmac_f32_e32 v147, v3, v135
	v_fmac_f32_e32 v148, v30, v139
	v_fmac_f32_e32 v149, v31, v139
	v_fmac_f32_e32 v150, v22, v143
	v_fmac_f32_e32 v151, v23, v143
	v_add_f32_e32 v144, v144, v146
	v_add_f32_e32 v145, v145, v147
	v_add_f32_e32 v148, v148, v150
	v_add_f32_e32 v149, v149, v151
	v_add_f32_e32 v144, v144, v148
	v_add_f32_e32 v145, v145, v149
	v_fma_f32 v152, -v17, v37, v144
	v_fma_f32 v153, v17, v36, v145
	v_fma_f32 v36, v16, v36, v152
	v_fma_f32 v37, v16, v37, v153
	ds_write_b32 v154, v36 offset:4752
	ds_write_b32 v154, v37 offset:5008
	ds_read_b128 v[128:131], v46 offset:9152
	ds_read_b128 v[132:135], v46 offset:9168
	ds_read_b128 v[136:139], v46 offset:9184
	ds_read_b128 v[140:143], v46 offset:9200
	s_waitcnt lgkmcnt(6)
	v_mul_f32_e32 v144, v12, v112
	v_mul_f32_e32 v145, v13, v112
	v_mul_f32_e32 v146, v4, v116
	v_mul_f32_e32 v147, v5, v116
	v_mul_f32_e32 v148, v32, v120
	v_mul_f32_e32 v149, v33, v120
	v_mul_f32_e32 v150, v24, v124
	v_mul_f32_e32 v151, v25, v124
	v_fmac_f32_e32 v144, v14, v113
	v_fmac_f32_e32 v145, v15, v113
	v_fmac_f32_e32 v146, v6, v117
	v_fmac_f32_e32 v147, v7, v117
	v_fmac_f32_e32 v148, v34, v121
	v_fmac_f32_e32 v149, v35, v121
	v_fmac_f32_e32 v150, v26, v125
	v_fmac_f32_e32 v151, v27, v125
	v_fmac_f32_e32 v144, v8, v114
	v_fmac_f32_e32 v145, v9, v114
	v_fmac_f32_e32 v146, v0, v118
	v_fmac_f32_e32 v147, v1, v118
	v_fmac_f32_e32 v148, v28, v122
	v_fmac_f32_e32 v149, v29, v122
	v_fmac_f32_e32 v150, v20, v126
	v_fmac_f32_e32 v151, v21, v126
	v_fmac_f32_e32 v144, v10, v115
	v_fmac_f32_e32 v145, v11, v115
	v_fmac_f32_e32 v146, v2, v119
	v_fmac_f32_e32 v147, v3, v119
	v_fmac_f32_e32 v148, v30, v123
	v_fmac_f32_e32 v149, v31, v123
	v_fmac_f32_e32 v150, v22, v127
	v_fmac_f32_e32 v151, v23, v127
	v_add_f32_e32 v144, v144, v146
	v_add_f32_e32 v145, v145, v147
	v_add_f32_e32 v148, v148, v150
	v_add_f32_e32 v149, v149, v151
	v_add_f32_e32 v144, v144, v148
	v_add_f32_e32 v145, v145, v149
	v_fma_f32 v152, -v17, v37, v144
	v_fma_f32 v153, v17, v36, v145
	v_fma_f32 v36, v16, v36, v152
	v_fma_f32 v37, v16, v37, v153
	ds_write_b32 v154, v36 offset:5280
	ds_write_b32 v154, v37 offset:5536
	ds_read_b128 v[112:115], v46 offset:9216
	ds_read_b128 v[116:119], v46 offset:9232
	ds_read_b128 v[120:123], v46 offset:9248
	ds_read_b128 v[124:127], v46 offset:9264
	s_waitcnt lgkmcnt(6)
; template <bool FULL>
; DI void ssm_item(const P& p, int l, int item, char* smem) {
;     ...
;     for (int t = 0; t < 16; ++t) {
;       const float4* up = (const float4*)(us + t * 16);
;       const float4 u0 = up[0], u1 = up[1], u2 = up[2], u3 = up[3];
;       const float uu[16] = {u0.x, u0.y, u0.z, u0.w, u1.x, u1.y, u1.z, u1.w, u2.x, u2.y, u2.z, u2.w, u3.x, u3.y, u3.z, u3.w};
;       float br = 0.f, bi = 0.f;
; #pragma unroll
;       for (int i = 0; i < 16; ++i) { br = fmaf(bbr[i], uu[i], br); bi = fmaf(bbi[i], uu[i], bi); }
;       const float nhr = ar * hr - ai * hi + br, nhi = ar * hi + ai * hr + bi;
;       hr = nhr; hi = nhi;
;       if (FULL) { H[t * 132 + lane] = hr; H[t * 132 + 64 + lane] = hi; }
;     }
	v_mul_f32_e32 v144, v12, v128
	v_mul_f32_e32 v145, v13, v128
	v_mul_f32_e32 v146, v4, v132
	v_mul_f32_e32 v147, v5, v132
	v_mul_f32_e32 v148, v32, v136
	v_mul_f32_e32 v149, v33, v136
	v_mul_f32_e32 v150, v24, v140
	v_mul_f32_e32 v151, v25, v140
	v_fmac_f32_e32 v144, v14, v129
	v_fmac_f32_e32 v145, v15, v129
	v_fmac_f32_e32 v146, v6, v133
	v_fmac_f32_e32 v147, v7, v133
	v_fmac_f32_e32 v148, v34, v137
	v_fmac_f32_e32 v149, v35, v137
	v_fmac_f32_e32 v150, v26, v141
	v_fmac_f32_e32 v151, v27, v141
	v_fmac_f32_e32 v144, v8, v130
	v_fmac_f32_e32 v145, v9, v130
	v_fmac_f32_e32 v146, v0, v134
	v_fmac_f32_e32 v147, v1, v134
	v_fmac_f32_e32 v148, v28, v138
	v_fmac_f32_e32 v149, v29, v138
	v_fmac_f32_e32 v150, v20, v142
	v_fmac_f32_e32 v151, v21, v142
	v_fmac_f32_e32 v144, v10, v131
	v_fmac_f32_e32 v145, v11, v131
	v_fmac_f32_e32 v146, v2, v135
	v_fmac_f32_e32 v147, v3, v135
	v_fmac_f32_e32 v148, v30, v139
	v_fmac_f32_e32 v149, v31, v139
	v_fmac_f32_e32 v150, v22, v143
	v_fmac_f32_e32 v151, v23, v143
	v_add_f32_e32 v144, v144, v146
	v_add_f32_e32 v145, v145, v147
	v_add_f32_e32 v148, v148, v150
	v_add_f32_e32 v149, v149, v151
	v_add_f32_e32 v144, v144, v148
	v_add_f32_e32 v145, v145, v149
	v_fma_f32 v152, -v17, v37, v144
	v_fma_f32 v153, v17, v36, v145
	v_fma_f32 v36, v16, v36, v152
	v_fma_f32 v37, v16, v37, v153
	ds_write_b32 v154, v36 offset:5808
	ds_write_b32 v154, v37 offset:6064
	ds_read_b128 v[128:131], v46 offset:9280
	ds_read_b128 v[132:135], v46 offset:9296
	ds_read_b128 v[136:139], v46 offset:9312
	ds_read_b128 v[140:143], v46 offset:9328
	s_waitcnt lgkmcnt(6)
	v_mul_f32_e32 v144, v12, v112
	v_mul_f32_e32 v145, v13, v112
	v_mul_f32_e32 v146, v4, v116
	v_mul_f32_e32 v147, v5, v116
	v_mul_f32_e32 v148, v32, v120
	v_mul_f32_e32 v149, v33, v120
	v_mul_f32_e32 v150, v24, v124
	v_mul_f32_e32 v151, v25, v124
	v_fmac_f32_e32 v144, v14, v113
	v_fmac_f32_e32 v145, v15, v113
	v_fmac_f32_e32 v146, v6, v117
	v_fmac_f32_e32 v147, v7, v117
	v_fmac_f32_e32 v148, v34, v121
	v_fmac_f32_e32 v149, v35, v121
	v_fmac_f32_e32 v150, v26, v125
	v_fmac_f32_e32 v151, v27, v125
	v_fmac_f32_e32 v144, v8, v114
	v_fmac_f32_e32 v145, v9, v114
	v_fmac_f32_e32 v146, v0, v118
	v_fmac_f32_e32 v147, v1, v118
	v_fmac_f32_e32 v148, v28, v122
	v_fmac_f32_e32 v149, v29, v122
	v_fmac_f32_e32 v150, v20, v126
	v_fmac_f32_e32 v151, v21, v126
	v_fmac_f32_e32 v144, v10, v115
	v_fmac_f32_e32 v145, v11, v115
	v_fmac_f32_e32 v146, v2, v119
	v_fmac_f32_e32 v147, v3, v119
	v_fmac_f32_e32 v148, v30, v123
	v_fmac_f32_e32 v149, v31, v123
	v_fmac_f32_e32 v150, v22, v127
	v_fmac_f32_e32 v151, v23, v127
	v_add_f32_e32 v144, v144, v146
	v_add_f32_e32 v145, v145, v147
	v_add_f32_e32 v148, v148, v150
	v_add_f32_e32 v149, v149, v151
	v_add_f32_e32 v144, v144, v148
	v_add_f32_e32 v145, v145, v149
	v_fma_f32 v152, -v17, v37, v144
	v_fma_f32 v153, v17, v36, v145
	v_fma_f32 v36, v16, v36, v152
	v_fma_f32 v37, v16, v37, v153
	ds_write_b32 v154, v36 offset:6336
	ds_write_b32 v154, v37 offset:6592
	ds_read_b128 v[112:115], v46 offset:9344
	ds_read_b128 v[116:119], v46 offset:9360
	ds_read_b128 v[120:123], v46 offset:9376
	ds_read_b128 v[124:127], v46 offset:9392
	s_waitcnt lgkmcnt(6)
	v_mul_f32_e32 v144, v12, v128
	v_mul_f32_e32 v145, v13, v128
	v_mul_f32_e32 v146, v4, v132
	v_mul_f32_e32 v147, v5, v132
	v_mul_f32_e32 v148, v32, v136
	v_mul_f32_e32 v149, v33, v136
	v_mul_f32_e32 v150, v24, v140
	v_mul_f32_e32 v151, v25, v140
	v_fmac_f32_e32 v144, v14, v129
	v_fmac_f32_e32 v145, v15, v129
	v_fmac_f32_e32 v146, v6, v133
	v_fmac_f32_e32 v147, v7, v133
	v_fmac_f32_e32 v148, v34, v137
	v_fmac_f32_e32 v149, v35, v137
	v_fmac_f32_e32 v150, v26, v141
	v_fmac_f32_e32 v151, v27, v141
	v_fmac_f32_e32 v144, v8, v130
	v_fmac_f32_e32 v145, v9, v130
	v_fmac_f32_e32 v146, v0, v134
	v_fmac_f32_e32 v147, v1, v134
	v_fmac_f32_e32 v148, v28, v138
	v_fmac_f32_e32 v149, v29, v138
	v_fmac_f32_e32 v150, v20, v142
	v_fmac_f32_e32 v151, v21, v142
	v_fmac_f32_e32 v144, v10, v131
	v_fmac_f32_e32 v145, v11, v131
	v_fmac_f32_e32 v146, v2, v135
	v_fmac_f32_e32 v147, v3, v135
	v_fmac_f32_e32 v148, v30, v139
	v_fmac_f32_e32 v149, v31, v139
	v_fmac_f32_e32 v150, v22, v143
	v_fmac_f32_e32 v151, v23, v143
	v_add_f32_e32 v144, v144, v146
	v_add_f32_e32 v145, v145, v147
	v_add_f32_e32 v148, v148, v150
	v_add_f32_e32 v149, v149, v151
	v_add_f32_e32 v144, v144, v148
	v_add_f32_e32 v145, v145, v149
	v_fma_f32 v152, -v17, v37, v144
	v_fma_f32 v153, v17, v36, v145
	v_fma_f32 v36, v16, v36, v152
	v_fma_f32 v37, v16, v37, v153
	ds_write_b32 v154, v36 offset:6864
	ds_write_b32 v154, v37 offset:7120
	ds_read_b128 v[128:131], v46 offset:9408
	ds_read_b128 v[132:135], v46 offset:9424
	ds_read_b128 v[136:139], v46 offset:9440
	ds_read_b128 v[140:143], v46 offset:9456
	s_waitcnt lgkmcnt(6)
	v_mul_f32_e32 v144, v12, v112
	v_mul_f32_e32 v145, v13, v112
	v_mul_f32_e32 v146, v4, v116
	v_mul_f32_e32 v147, v5, v116
	v_mul_f32_e32 v148, v32, v120
	v_mul_f32_e32 v149, v33, v120
	v_mul_f32_e32 v150, v24, v124
	v_mul_f32_e32 v151, v25, v124
	v_fmac_f32_e32 v144, v14, v113
	v_fmac_f32_e32 v145, v15, v113
	v_fmac_f32_e32 v146, v6, v117
	v_fmac_f32_e32 v147, v7, v117
	v_fmac_f32_e32 v148, v34, v121
	v_fmac_f32_e32 v149, v35, v121
	v_fmac_f32_e32 v150, v26, v125
	v_fmac_f32_e32 v151, v27, v125
	v_fmac_f32_e32 v144, v8, v114
	v_fmac_f32_e32 v145, v9, v114
	v_fmac_f32_e32 v146, v0, v118
	v_fmac_f32_e32 v147, v1, v118
	v_fmac_f32_e32 v148, v28, v122
	v_fmac_f32_e32 v149, v29, v122
	v_fmac_f32_e32 v150, v20, v126
	v_fmac_f32_e32 v151, v21, v126
	v_fmac_f32_e32 v144, v10, v115
	v_fmac_f32_e32 v145, v11, v115
	v_fmac_f32_e32 v146, v2, v119
	v_fmac_f32_e32 v147, v3, v119
	v_fmac_f32_e32 v148, v30, v123
	v_fmac_f32_e32 v149, v31, v123
	v_fmac_f32_e32 v150, v22, v127
	v_fmac_f32_e32 v151, v23, v127
	v_add_f32_e32 v144, v144, v146
	v_add_f32_e32 v145, v145, v147
	v_add_f32_e32 v148, v148, v150
	v_add_f32_e32 v149, v149, v151
	v_add_f32_e32 v144, v144, v148
	v_add_f32_e32 v145, v145, v149
	v_fma_f32 v152, -v17, v37, v144
	v_fma_f32 v153, v17, v36, v145
	v_fma_f32 v36, v16, v36, v152
	v_fma_f32 v37, v16, v37, v153
	ds_write_b32 v154, v36 offset:7392
	ds_write_b32 v154, v37 offset:7648
	s_waitcnt lgkmcnt(2)
; DI float sigm(float x) { return __builtin_amdgcn_rcpf(1.f + __expf(-x)); }
; template <bool FULL>
; DI void ssm_item(const P& p, int l, int item, char* smem) {
;     ...
;     for (int t = 0; t < 16; ++t) {
;       const float4* up = (const float4*)(us + t * 16);
;       const float4 u0 = up[0], u1 = up[1], u2 = up[2], u3 = up[3];
;       const float uu[16] = {u0.x, u0.y, u0.z, u0.w, u1.x, u1.y, u1.z, u1.w, u2.x, u2.y, u2.z, u2.w, u3.x, u3.y, u3.z, u3.w};
;       float br = 0.f, bi = 0.f;
; #pragma unroll
;       for (int i = 0; i < 16; ++i) { br = fmaf(bbr[i], uu[i], br); bi = fmaf(bbi[i], uu[i], bi); }
;       const float nhr = ar * hr - ai * hi + br, nhi = ar * hi + ai * hr + bi;
;       hr = nhr; hi = nhi;
;       if (FULL) { H[t * 132 + lane] = hr; H[t * 132 + 64 + lane] = hi; }
;     }
;     if (FULL) {
;       __builtin_amdgcn_wave_barrier();
;       f32x4 acc = {0.f, 0.f, 0.f, 0.f};
;       const float* hp = H + ch * 132 + quad * 32;
; #pragma unroll
;       for (int i = 0; i < 8; ++i) {
;         const float4 hv = *(const float4*)(hp + 4 * i);
;         acc = __builtin_amdgcn_mfma_f32_16x16x4f32(hv.x, creg[4 * i], acc, 0, 0, 0);
;         acc = __builtin_amdgcn_mfma_f32_16x16x4f32(hv.y, creg[4 * i + 1], acc, 0, 0, 0);
;         acc = __builtin_amdgcn_mfma_f32_16x16x4f32(hv.z, creg[4 * i + 2], acc, 0, 0, 0);
;         acc = __builtin_amdgcn_mfma_f32_16x16x4f32(hv.w, creg[4 * i + 3], acc, 0, 0, 0);
;       }
; #pragma unroll
;       for (int r = 0; r < 4; ++r) {
;         const int tl = quad * 4 + r;
;         float y = acc[r] + dsk * us[tl * 16 + ch];
;         const float y3 = y * y * y;
;         y = y * sigm(1.5957691216057308f * (y + 0.044715f * y3));
;         p.y_pre[(tok0 + s * 16 + tl) * 512 + g * 16 + ch] = f2bf(y);
;       }
	v_mul_f32_e32 v144, v12, v128
	v_mul_f32_e32 v145, v13, v128
	v_mul_f32_e32 v146, v4, v132
	v_mul_f32_e32 v147, v5, v132
	v_mul_f32_e32 v148, v32, v136
	v_mul_f32_e32 v149, v33, v136
	v_mul_f32_e32 v150, v24, v140
	v_mul_f32_e32 v151, v25, v140
	v_fmac_f32_e32 v144, v14, v129
	v_fmac_f32_e32 v145, v15, v129
	v_fmac_f32_e32 v146, v6, v133
	v_fmac_f32_e32 v147, v7, v133
	v_fmac_f32_e32 v148, v34, v137
	v_fmac_f32_e32 v149, v35, v137
	v_fmac_f32_e32 v150, v26, v141
	v_fmac_f32_e32 v151, v27, v141
	v_fmac_f32_e32 v144, v8, v130
	v_fmac_f32_e32 v145, v9, v130
	v_fmac_f32_e32 v146, v0, v134
	v_fmac_f32_e32 v147, v1, v134
	v_fmac_f32_e32 v148, v28, v138
	v_fmac_f32_e32 v149, v29, v138
	v_fmac_f32_e32 v150, v20, v142
	v_fmac_f32_e32 v151, v21, v142
	v_fmac_f32_e32 v144, v10, v131
	v_fmac_f32_e32 v145, v11, v131
	v_fmac_f32_e32 v146, v2, v135
	v_fmac_f32_e32 v147, v3, v135
	v_fmac_f32_e32 v148, v30, v139
	v_fmac_f32_e32 v149, v31, v139
	v_fmac_f32_e32 v150, v22, v143
	v_fmac_f32_e32 v151, v23, v143
	v_add_f32_e32 v144, v144, v146
	v_add_f32_e32 v145, v145, v147
	v_add_f32_e32 v148, v148, v150
	v_add_f32_e32 v149, v149, v151
	v_add_f32_e32 v144, v144, v148
	v_add_f32_e32 v145, v145, v149
	v_fma_f32 v152, -v17, v37, v144
	v_fma_f32 v153, v17, v36, v145
	v_fma_f32 v36, v16, v36, v152
	v_fma_f32 v37, v16, v37, v153
	ds_write_b32 v154, v36 offset:7920
	ds_write_b32 v154, v37 offset:8176
	ds_read_b128 v[112:115], v81
	ds_read_b128 v[116:119], v81 offset:16
	ds_read_b128 v[120:123], v81 offset:32
	ds_read_b128 v[124:127], v81 offset:48
	ds_read_b128 v[128:131], v81 offset:64
	ds_read_b128 v[132:135], v81 offset:80
	ds_read_b128 v[136:139], v81 offset:96
	ds_read_b128 v[140:143], v81 offset:112
	ds_read_b32 v91, v87 offset:8448
	ds_read_b32 v106, v88 offset:8448
	ds_read_b32 v107, v89 offset:8448
	ds_read_b32 v108, v90 offset:8448
	s_lshl_b32 s7, s7, 4
	v_lshrrev_b32_e32 v155, 2, v86
	v_and_b32_e32 v160, 15, v155
	v_lshlrev_b32_e32 v162, 1, v160
	v_lshrrev_b32_e32 v161, 4, v155
	v_lshl_add_u32 v163, v161, 7, v162
	v_add_u32_e32 v163, v46, v163
	v_lshl_add_u32 v164, v155, 4, v46
	v_and_b32_e32 v165, 1, v155
	v_lshlrev_b32_e32 v165, 4, v165
	v_sub_u32_e32 v168, v165, v162
	v_ashrrev_i32_e32 v169, 31, v168
	v_lshl_add_u64 v[168:169], v[42:43], 0, v[168:169]
	v_lshrrev_b32_e32 v170, 1, v155
	v_or_b32_e32 v170, s7, v170
	v_or_b32_e32 v170, s0, v170
	v_mov_b32_e32 v171, s1
	v_lshlrev_b64 v[170:171], 10, v[170:171]
	v_lshl_add_u64 v[168:169], v[168:169], 0, v[170:171]
	s_cmp_eq_u32 s6, 8
	s_mov_b32 s7, s6
	s_waitcnt lgkmcnt(10)
	v_mfma_f32_16x16x4_f32 v[100:103], v112, v47, 0
	v_mfma_f32_16x16x4_f32 v[144:147], v116, v51, 0
	v_mfma_f32_16x16x4_f32 v[100:103], v113, v48, v[100:103]
	v_mfma_f32_16x16x4_f32 v[144:147], v117, v52, v[144:147]
	v_mfma_f32_16x16x4_f32 v[100:103], v114, v49, v[100:103]
	v_mfma_f32_16x16x4_f32 v[144:147], v118, v53, v[144:147]
	v_mfma_f32_16x16x4_f32 v[100:103], v115, v50, v[100:103]
	v_mfma_f32_16x16x4_f32 v[144:147], v119, v54, v[144:147]
	s_waitcnt lgkmcnt(8)
	v_mfma_f32_16x16x4_f32 v[100:103], v120, v55, v[100:103]
	v_mfma_f32_16x16x4_f32 v[144:147], v124, v59, v[144:147]
	v_mfma_f32_16x16x4_f32 v[100:103], v121, v56, v[100:103]
	v_mfma_f32_16x16x4_f32 v[144:147], v125, v60, v[144:147]
	v_mfma_f32_16x16x4_f32 v[100:103], v122, v57, v[100:103]
	v_mfma_f32_16x16x4_f32 v[144:147], v126, v61, v[144:147]
	v_mfma_f32_16x16x4_f32 v[100:103], v123, v58, v[100:103]
	v_mfma_f32_16x16x4_f32 v[144:147], v127, v62, v[144:147]
	s_waitcnt lgkmcnt(6)
	v_mfma_f32_16x16x4_f32 v[100:103], v128, v63, v[100:103]
	v_mfma_f32_16x16x4_f32 v[144:147], v132, v67, v[144:147]
	v_mfma_f32_16x16x4_f32 v[100:103], v129, v64, v[100:103]
	v_mfma_f32_16x16x4_f32 v[144:147], v133, v68, v[144:147]
	v_mfma_f32_16x16x4_f32 v[100:103], v130, v65, v[100:103]
	v_mfma_f32_16x16x4_f32 v[144:147], v134, v69, v[144:147]
	v_mfma_f32_16x16x4_f32 v[100:103], v131, v66, v[100:103]
	v_mfma_f32_16x16x4_f32 v[144:147], v135, v70, v[144:147]
	s_waitcnt lgkmcnt(4)
	v_mfma_f32_16x16x4_f32 v[100:103], v136, v71, v[100:103]
	v_mfma_f32_16x16x4_f32 v[144:147], v140, v75, v[144:147]
	v_mfma_f32_16x16x4_f32 v[100:103], v137, v72, v[100:103]
	v_mfma_f32_16x16x4_f32 v[144:147], v141, v76, v[144:147]
	v_mfma_f32_16x16x4_f32 v[100:103], v138, v73, v[100:103]
	v_mfma_f32_16x16x4_f32 v[144:147], v142, v77, v[144:147]
	v_mfma_f32_16x16x4_f32 v[100:103], v139, v74, v[100:103]
	v_mfma_f32_16x16x4_f32 v[144:147], v143, v78, v[144:147]
	s_nop 9
	v_add_f32_e32 v92, v100, v144
	v_add_f32_e32 v93, v101, v145
	v_add_f32_e32 v94, v102, v146
	v_add_f32_e32 v95, v103, v147
	s_waitcnt lgkmcnt(3)
	s_nop 0
	v_fma_f32 v91, v79, v91, v92
	s_waitcnt lgkmcnt(2)
	v_fma_f32 v92, v79, v106, v93
	s_waitcnt lgkmcnt(1)
	v_fma_f32 v93, v79, v107, v94
	s_waitcnt lgkmcnt(0)
	v_fmac_f32_e32 v95, v79, v108
	v_mul_f32_e32 v94, v91, v91
	v_mul_f32_e32 v102, v92, v92
	v_mul_f32_e32 v103, v93, v93
	v_mul_f32_e32 v106, v95, v95
	v_mul_f32_e32 v94, v91, v94
	v_mul_f32_e32 v102, v92, v102
	v_mul_f32_e32 v103, v93, v103
	v_mul_f32_e32 v106, v95, v106
	v_fmamk_f32 v94, v94, 0x3d372713, v91
	v_fmamk_f32 v102, v102, 0x3d372713, v92
	v_fmamk_f32 v103, v103, 0x3d372713, v93
	v_fmamk_f32 v106, v106, 0x3d372713, v95
	v_mul_f32_e32 v94, 0x3fcc422a, v94
	v_mul_f32_e32 v102, 0x3fcc422a, v102
	v_mul_f32_e32 v103, 0x3fcc422a, v103
	v_mul_f32_e32 v106, 0x3fcc422a, v106
	v_mul_f32_e32 v94, 0xbfb8aa3b, v94
	v_mul_f32_e32 v102, 0xbfb8aa3b, v102
	v_mul_f32_e32 v103, 0xbfb8aa3b, v103
	v_mul_f32_e32 v106, 0xbfb8aa3b, v106
	v_exp_f32_e32 v94, v94
	v_exp_f32_e32 v102, v102
	v_exp_f32_e32 v103, v103
	v_exp_f32_e32 v106, v106
	v_add_f32_e32 v94, 1.0, v94
	v_add_f32_e32 v102, 1.0, v102
	v_add_f32_e32 v103, 1.0, v103
	v_add_f32_e32 v106, 1.0, v106
	v_rcp_f32_e32 v94, v94
	v_rcp_f32_e32 v102, v102
	v_rcp_f32_e32 v103, v103
	v_rcp_f32_e32 v106, v106
	v_mul_f32_e32 v91, v91, v94
	v_mul_f32_e32 v92, v92, v102
	v_mul_f32_e32 v93, v93, v103
	v_mul_f32_e32 v94, v95, v106
	v_cvt_pk_bf16_f32 v91, v91, s0
	v_cvt_pk_bf16_f32 v92, v92, s0
	v_cvt_pk_bf16_f32 v93, v93, s0
	v_cvt_pk_bf16_f32 v94, v94, s0
	ds_write_b16 v163, v91
	ds_write_b16 v163, v92 offset:32
	ds_write_b16 v163, v93 offset:64
	ds_write_b16 v163, v94 offset:96
	ds_read_b128 v[156:159], v164
	s_mov_b64 s[8:9], exec
	s_mov_b32 exec_lo, -1
	s_mov_b32 exec_hi, 0
	s_waitcnt lgkmcnt(0)
	global_store_dwordx4 v[168:169], v[156:159], off
	s_mov_b64 exec, s[8:9]
	s_cbranch_scc0 .LBB0_170
	v_readlane_b32 s0, v249, 5
	s_add_i32 s21, s21, s0
	v_readlane_b32 s0, v250, 62
	s_add_i32 s20, s20, s0
	s_cmpk_gt_i32 s21, 0xfff
	v_readlane_b32 s1, v249, 6
	s_cbranch_scc0 .LBB0_165

; DI void attn_item(const P& p, int b, int kvh, int quad4, char* smem, const AttnPre& pre) {
;     ...
;   __builtin_amdgcn_wave_barrier();
;   if (t < 256) {
; #pragma unroll
;     for (int j = 0; j < 4; ++j) { const int n = lane + 64 * j; idx[n] = n < cnt ? n : 0; }
;   } else {
;     const uint2 sv = pre.sv;
;     idx[lane * 4 + 0] = sv.x & 0xffff; idx[lane * 4 + 1] = sv.x >> 16; idx[lane * 4 + 2] = sv.y & 0xffff; idx[lane * 4 + 3] = sv.y >> 16;
;   }
.LBB0_309:
	s_waitcnt lgkmcnt(14)
	v_mov_b32_e32 v35, v218
	s_lshl_b32 s4, s6, 2
	s_and_b32 s4, s4, 0x1ffc
	v_ashrrev_i32_e32 v34, 6, v35
	v_add_u32_e32 v90, s4, v34
	s_movk_i32 s4, 0x1400
	v_mul_lo_u32 v103, v34, s4
	v_and_b32_e32 v102, 63, v35
	v_add_u32_e32 v34, 0, v103
	s_movk_i32 s4, 0xff
	v_cmp_lt_i32_e32 vcc, s4, v90
	v_lshl_add_u32 v104, v102, 4, v34
	s_and_saveexec_b64 s[4:5], vcc
	s_xor_b64 s[4:5], exec, s[4:5]
	s_cbranch_execz .LBB0_311
	s_waitcnt vmcnt(4)
	v_and_b32_e32 v36, 0xffff, v32
	v_lshrrev_b32_e32 v37, 16, v32
	v_and_b32_e32 v38, 0xffff, v33
	v_lshrrev_b32_e32 v39, 16, v33
	ds_write_b128 v104, v[36:39] offset:4096

; DI void attn_item(const P& p, int b, int kvh, int quad4, char* smem, const AttnPre& pre) {
;     ...
;   const int r = lane & 15, quad = lane >> 4;
;   long qa8[4];
;   {
;     const bf16_t* qp = p.q + tok * 1024 + (kvh * 4 + (r & 3)) * 128 + quad * 16;
; #pragma unroll
;     for (int s = 0; s < 4; ++s) {
;       const u32x4 tq = pre.tq[s];
;       float f[8];
; #pragma unroll
;       for (int e = 0; e < 4; ++e) { f[2 * e] = __uint_as_float(tq[e] << 16); f[2 * e + 1] = __uint_as_float(tq[e] & 0xffff0000u); }
;       const uint2 pk = pack8_fp8(f);
;       long v = (long)(((unsigned long long)pk.y << 32) | (unsigned long long)pk.x);
;       if (r >= 4) v = 0;
;       qa8[s] = v;
;     }
;   }
;   __builtin_amdgcn_wave_barrier();
;   const unsigned char* kb = p.k8 + ((size_t)b * SEQ) * 256 + kvh * 128 + quad * 16;
;   int myidx[16];
; #pragma unroll
;   for (int kt = 0; kt < 16; ++kt) myidx[kt] = idx[kt * 16 + r];
; #pragma unroll
;   for (int kt0 = 0; kt0 < 16; kt0 += 8) {
;     u32x4 kraw[8][2];
; #pragma unroll
;     for (int u = 0; u < 8; ++u) {
;       const unsigned char* kp = kb + (size_t)myidx[kt0 + u] * 256;
;       kraw[u][0] = *(const u32x4*)kp; kraw[u][1] = *(const u32x4*)(kp + 64);
;     }
; #pragma unroll
;     for (int u = 0; u < 8; ++u) {
;       const int n = (kt0 + u) * 16 + r;
;       f32x4 acc = {0.f, 0.f, 0.f, 0.f};
; #pragma unroll
;       for (int S = 0; S < 2; ++S) {
;         const long k0 = (long)(((unsigned long long)kraw[u][S][1] << 32) | (unsigned long long)kraw[u][S][0]);
;         const long k1 = (long)(((unsigned long long)kraw[u][S][3] << 32) | (unsigned long long)kraw[u][S][2]);
;         acc = __builtin_amdgcn_mfma_f32_16x16x32_fp8_fp8(qa8[2 * S], k0, acc, 0, 0, 0);
;         acc = __builtin_amdgcn_mfma_f32_16x16x32_fp8_fp8(qa8[2 * S + 1], k1, acc, 0, 0, 0);
;       }
.LBB0_313:
	s_or_b64 exec, exec, s[4:5]
	v_and_b32_e32 v105, 15, v35
	v_lshl_add_u32 v108, v105, 2, v34
	v_add_u32_e32 v109, 0x1000, v108
	v_and_b32_e32 v192, 48, v35
	s_waitcnt vmcnt(4)
	ds_read2_b32 v[32:33], v109 offset1:16
	ds_read2_b32 v[34:35], v109 offset0:32 offset1:48
	s_ashr_i32 s9, s6, 11
	ds_read2_b32 v[40:41], v109 offset0:64 offset1:80
	s_lshl_b32 s10, s9, 7
	s_waitcnt vmcnt(4) lgkmcnt(2)
	v_ashrrev_i32_e32 v37, 31, v32
	v_mov_b32_e32 v36, v32
	v_ashrrev_i32_e32 v39, 31, v33
	v_mov_b32_e32 v38, v33
	s_waitcnt lgkmcnt(1)
	v_ashrrev_i32_e32 v33, 31, v34
	v_mov_b32_e32 v32, v34
	v_ashrrev_i32_e32 v43, 31, v35
	v_mov_b32_e32 v42, v35
	ds_read2_b32 v[34:35], v109 offset0:96 offset1:112
	s_ashr_i32 s11, s10, 31
	v_readlane_b32 s4, v250, 13
	s_add_u32 s4, s4, s10
	v_readlane_b32 s5, v250, 14
	s_addc_u32 s5, s5, s11
	s_waitcnt lgkmcnt(1)
	v_ashrrev_i32_e32 v45, 31, v40
	v_mov_b32_e32 v44, v40
	v_ashrrev_i32_e32 v47, 31, v41
	v_mov_b32_e32 v46, v41
	s_waitcnt lgkmcnt(0)
	v_ashrrev_i32_e32 v41, 31, v34
	v_mov_b32_e32 v40, v34
	v_ashrrev_i32_e32 v93, 31, v35
	v_mov_b32_e32 v92, v35
	v_lshl_add_u64 v[100:101], s[4:5], 0, v[192:193]
	v_lshlrev_b64 v[34:35], 8, v[36:37]
	v_lshl_add_u64 v[34:35], v[100:101], 0, v[34:35]
	global_load_dwordx4 v[110:113], v[34:35], off
	global_load_dwordx4 v[114:117], v[34:35], off offset:64
	v_lshlrev_b64 v[34:35], 8, v[38:39]
	v_lshlrev_b64 v[32:33], 8, v[32:33]
	v_lshl_add_u64 v[34:35], v[100:101], 0, v[34:35]
	v_lshl_add_u64 v[32:33], v[100:101], 0, v[32:33]
	global_load_dwordx4 v[84:87], v[34:35], off
	global_load_dwordx4 v[80:83], v[34:35], off offset:64
	global_load_dwordx4 v[76:79], v[32:33], off
	global_load_dwordx4 v[72:75], v[32:33], off offset:64
	v_lshlrev_b64 v[32:33], 8, v[42:43]
	v_lshl_add_u64 v[32:33], v[100:101], 0, v[32:33]
	global_load_dwordx4 v[68:71], v[32:33], off
	global_load_dwordx4 v[64:67], v[32:33], off offset:64
	v_lshlrev_b64 v[32:33], 8, v[44:45]
	v_lshl_add_u64 v[32:33], v[100:101], 0, v[32:33]
	global_load_dwordx4 v[60:63], v[32:33], off
	global_load_dwordx4 v[56:59], v[32:33], off offset:64
	v_lshlrev_b64 v[32:33], 8, v[46:47]
	v_lshl_add_u64 v[32:33], v[100:101], 0, v[32:33]
	global_load_dwordx4 v[52:55], v[32:33], off
	global_load_dwordx4 v[48:51], v[32:33], off offset:64
	v_lshlrev_b64 v[32:33], 8, v[40:41]
	v_lshl_add_u64 v[32:33], v[100:101], 0, v[32:33]
	global_load_dwordx4 v[44:47], v[32:33], off
	global_load_dwordx4 v[40:43], v[32:33], off offset:64
	v_lshlrev_b64 v[32:33], 8, v[92:93]
	v_lshl_add_u64 v[32:33], v[100:101], 0, v[32:33]
	global_load_dwordx4 v[36:39], v[32:33], off
	s_nop 0
	global_load_dwordx4 v[32:35], v[32:33], off offset:64
	s_waitcnt vmcnt(18)
	v_lshlrev_b32_e32 v92, 16, v28
	v_and_b32_e32 v28, 0xffff0000, v28
	v_mov_b32_e32 v95, v193
	v_lshlrev_b32_e32 v94, 16, v30
	v_and_b32_e32 v30, 0xffff0000, v30
	v_cvt_pk_fp8_f32 v95, v92, v28
	v_mov_b32_e32 v28, v193
	v_cvt_pk_fp8_f32 v28, v94, v30
	v_lshlrev_b32_e32 v93, 16, v29
	v_and_b32_e32 v29, 0xffff0000, v29
	v_lshlrev_b32_e32 v30, 16, v31
	v_and_b32_e32 v31, 0xffff0000, v31
	v_cvt_pk_fp8_f32 v95, v93, v29 op_sel:[0,0,1]
	v_lshlrev_b32_e32 v29, 16, v24
	v_and_b32_e32 v24, 0xffff0000, v24
	v_mov_b32_e32 v94, v193
	v_cvt_pk_fp8_f32 v28, v30, v31 op_sel:[0,0,1]
	v_lshlrev_b32_e32 v31, 16, v26
	v_and_b32_e32 v26, 0xffff0000, v26
	v_cvt_pk_fp8_f32 v94, v29, v24
	v_mov_b32_e32 v24, v193
	v_cvt_pk_fp8_f32 v24, v31, v26
	v_lshlrev_b32_e32 v26, 16, v27
	v_and_b32_e32 v27, 0xffff0000, v27
	v_lshlrev_b32_e32 v30, 16, v25
	v_cvt_pk_fp8_f32 v24, v26, v27 op_sel:[0,0,1]
	v_and_b32_e32 v25, 0xffff0000, v25
	v_cvt_pk_fp8_f32 v94, v30, v25 op_sel:[0,0,1]
	v_cmp_lt_u32_e32 vcc, 3, v105
	s_waitcnt vmcnt(16)
	v_lshlrev_b32_e32 v25, 16, v22
	v_and_b32_e32 v22, 0xffff0000, v22
	v_mov_b32_e32 v27, v193
	v_cndmask_b32_e64 v92, v95, 0, vcc
	v_cndmask_b32_e64 v95, v24, 0, vcc
	v_lshlrev_b32_e32 v24, 16, v20
	v_and_b32_e32 v20, 0xffff0000, v20
	v_lshlrev_b32_e32 v26, 16, v23
	v_cvt_pk_fp8_f32 v27, v25, v22
	v_and_b32_e32 v22, 0xffff0000, v23
	v_mov_b32_e32 v23, v193
	v_cvt_pk_fp8_f32 v23, v24, v20
	v_lshlrev_b32_e32 v20, 16, v21
	v_and_b32_e32 v21, 0xffff0000, v21
	v_cndmask_b32_e64 v93, v28, 0, vcc
	v_cvt_pk_fp8_f32 v27, v26, v22 op_sel:[0,0,1]
	v_cvt_pk_fp8_f32 v23, v20, v21 op_sel:[0,0,1]
	v_lshlrev_b32_e32 v21, 16, v17
	v_and_b32_e32 v22, 0xffff0000, v17
	v_lshlrev_b32_e32 v17, 16, v18
	v_and_b32_e32 v18, 0xffff0000, v18
	v_mov_b32_e32 v25, v193
	v_cvt_pk_fp8_f32 v25, v17, v18
	v_lshlrev_b32_e32 v20, 16, v16
	v_and_b32_e32 v16, 0xffff0000, v16
	v_mov_b32_e32 v26, v193
	v_cndmask_b32_e64 v94, v94, 0, vcc
	v_lshlrev_b32_e32 v24, 16, v19
	v_cvt_pk_fp8_f32 v26, v20, v16
	v_and_b32_e32 v16, 0xffff0000, v19
	v_cvt_pk_fp8_f32 v25, v24, v16 op_sel:[0,0,1]
	s_waitcnt vmcnt(15)
	v_mfma_f32_16x16x32_fp8_fp8 v[16:19], v[92:93], v[110:111], 0
	v_cndmask_b32_e64 v97, v27, 0, vcc
	v_cvt_pk_fp8_f32 v26, v21, v22 op_sel:[0,0,1]
	v_cndmask_b32_e64 v96, v23, 0, vcc
	v_mfma_f32_16x16x32_fp8_fp8 v[16:19], v[94:95], v[112:113], v[16:19]
	v_cndmask_b32_e64 v99, v25, 0, vcc
	v_cndmask_b32_e64 v98, v26, 0, vcc
	ds_read2_b32 v[26:27], v109 offset0:128 offset1:144
	ds_read2_b32 v[24:25], v109 offset0:160 offset1:176
	s_waitcnt vmcnt(14)
	v_mfma_f32_16x16x32_fp8_fp8 v[16:19], v[96:97], v[114:115], v[16:19]
	ds_read2_b32 v[22:23], v109 offset0:192 offset1:208
	ds_read2_b32 v[20:21], v109 offset0:224 offset1:240
	v_cmp_gt_u32_e64 s[4:5], 16, v102
	v_mfma_f32_16x16x32_fp8_fp8 v[16:19], v[98:99], v[116:117], v[16:19]
	s_and_saveexec_b64 s[6:7], s[4:5]
	s_cbranch_execz .LBB0_315
	s_nop 5
	v_mul_f32_e32 v16, 0x3db504f3, v16
	v_cmp_lt_i32_e32 vcc, v90, v105
	v_mul_f32_e32 v17, 0x3db504f3, v17
	s_nop 0
	v_cndmask_b32_e32 v16, v16, v224, vcc
	v_cndmask_b32_e32 v17, v17, v224, vcc
	ds_write2st64_b32 v108, v16, v17 offset1:4
	v_mul_f32_e32 v16, 0x3db504f3, v18
	v_mul_f32_e32 v17, 0x3db504f3, v19
	v_cndmask_b32_e32 v16, v16, v224, vcc
	v_cndmask_b32_e32 v17, v17, v224, vcc
	ds_write2st64_b32 v108, v16, v17 offset0:8 offset1:12
